# slot table T10: ph0 gate/up slot 1 round, down slots 4 rounds
# baseline (speedup 1.0000x reference)
; __device__ void phase_convert(PP p, unsigned char* smem) {
;     ...
;   int t = blockIdx.x;
;   if (t < NT_ALL) {
;     cvt_decode(p, t, src, ld, dst, K, k0, n0, n4);
; #pragma unroll
;     for (int i = 0; i < 4; ++i) cur[i] = src ? *(const f32x4*)(src + (size_t)(kl + 16 * i) * ld) : (f32x4){0.f, 0.f, 0.f, 0.f};
;   }
;   for (; t < NT_ALL; t += gridDim.x) {
;     const int tn = t + gridDim.x;
;     const float* src2 = nullptr; int ld2 = 0, K2, k02, n02; bf16_t* dst2;
.Lcvt_t0:
	s_mov_b32 s98, 208
	s_mov_b32 s99, 416
	s_mov_b32 s100, 48
	s_branch .Lcvt_go
.Lcvt_t1:
	s_mov_b32 s98, 416
	s_mov_b32 s99, 928
	s_mov_b32 s100, 128
	s_branch .Lcvt_go
.Lcvt_t3:
	s_mov_b32 s98, 928
	s_mov_b32 s99, 1672
	s_mov_b32 s100, 132
	s_branch .Lcvt_go
.Lcvt_t7:
	s_mov_b32 s98, 1672
	s_mov_b32 s99, 1800
	s_mov_b32 s100, 128
	s_branch .Lcvt_go
.Lcvt_t9:
	s_mov_b32 s98, 1800
	s_mov_b32 s99, 2216
	s_mov_b32 s100, 48
	s_branch .Lcvt_go
.Lcvt_t10:
	s_mov_b32 s98, 2216
	s_mov_b32 s99, 2728
	s_mov_b32 s100, 128
	s_branch .Lcvt_go
.Lcvt_t12:
	s_mov_b32 s98, 2728
	s_mov_b32 s99, 3144
	s_mov_b32 s100, 48
	s_branch .Lcvt_go
.Lcvt_t13:
	s_mov_b32 s98, 3144
	s_mov_b32 s99, 3656
	s_mov_b32 s100, 128
	s_branch .Lcvt_go
.Lcvt_t15:
	s_mov_b32 s98, 3656
	s_mov_b32 s99, 4224
	s_mov_b32 s100, 132
	s_branch .Lcvt_go
